# code placement: selected-branch loop shifted by 4 bytes so most of its 8-byte instructions start on 8-byte boundaries (58 of 91 instead of 33), downstream code kept at its old phase
# speedup vs baseline: 1.0020x; 1.0020x over previous
.LBB0_625:
	v_mov_b32_e32 v0, 0x1400000
	s_add_i32 s82, s18, s16
	v_mad_i64_i32 v[2:3], s[4:5], s16, v0, v[154:155]
	s_ashr_i32 s83, s82, 31
	s_lshl_b32 s74, s24, 7
	s_lshl_b64 s[4:5], s[82:83], 19
	s_waitcnt lgkmcnt(0)
	v_lshl_add_u64 v[148:149], v[2:3], 0, s[74:75]
	v_lshl_add_u64 v[2:3], v[164:165], 0, s[4:5]
	s_lshl_b64 s[4:5], 2, s17
	ds_read_b64 v[152:153], v37 offset:18432
	s_waitcnt lgkmcnt(0)
	s_add_u32 s4, s4, -1
	v_and_b32_e32 v8, 31, v195
	v_ashrrev_i32_e32 v9, 5, v195
	s_addc_u32 s5, s5, -1
	v_mul_u32_u24_e32 v0, 0xa00, v8
	v_lshlrev_b32_e32 v6, 3, v9
	s_and_b64 s[94:95], s[20:21], s[4:5]
	v_lshlrev_b32_e32 v0, 1, v0
	v_ashrrev_i32_e32 v7, 31, v6
	v_lshl_add_u64 v[4:5], v[148:149], 0, v[0:1]
	v_lshlrev_b64 v[6:7], 1, v[6:7]
	s_ff1_i32_b64 s4, s[94:95]
	v_lshl_add_u64 v[180:181], v[4:5], 0, v[6:7]
	v_lshl_add_u64 v[2:3], v[2:3], 0, v[6:7]
	v_lshlrev_b32_e32 v0, 5, v8
	v_mov_b32_e32 v14, v1
	v_mov_b32_e32 v15, v1
	v_lshl_add_u64 v[182:183], v[2:3], 0, v[0:1]
	s_mov_b64 s[100:101], 0x1400000
	s_mov_b32 s99, 0
	v_lshl_add_u64 v[240:241], v[182:183], 0, s[100:101]
	s_lshl_b32 s74, s4, 13
	v_lshl_add_u64 v[4:5], v[240:241], 0, s[74:75]
	global_load_dwordx4 v[118:121], v[4:5], off
	global_load_dwordx4 v[122:125], v[4:5], off offset:1024
	global_load_dwordx4 v[126:129], v[4:5], off offset:2048
	global_load_dwordx4 v[114:117], v[4:5], off offset:3072
	v_lshlrev_b32_e32 v173, 2, v9
	v_mov_b32_e32 v0, v1
	v_mov_b32_e32 v2, v1
	v_mov_b32_e32 v3, v1
	v_mov_b32_e32 v4, v1
	v_mov_b32_e32 v5, v1
	v_mov_b32_e32 v6, v1
	v_mov_b32_e32 v7, v1
	v_mov_b32_e32 v8, v1
	v_mov_b32_e32 v9, v1
	v_mov_b32_e32 v10, v1
	v_mov_b32_e32 v11, v1
	v_mov_b32_e32 v12, v1
	v_mov_b32_e32 v13, v1
	v_mov_b64_e32 v[64:65], v[14:15]
	v_mov_b64_e32 v[48:49], v[14:15]
	v_mov_b64_e32 v[32:33], v[14:15]
	v_mov_b32_e32 v151, 0
	v_mov_b64_e32 v[62:63], v[12:13]
	v_mov_b64_e32 v[60:61], v[10:11]
	v_mov_b64_e32 v[58:59], v[8:9]
	v_mov_b64_e32 v[56:57], v[6:7]
	v_mov_b64_e32 v[54:55], v[4:5]
	v_mov_b64_e32 v[52:53], v[2:3]
	v_mov_b64_e32 v[50:51], v[0:1]
	v_mov_b64_e32 v[46:47], v[12:13]
	v_mov_b64_e32 v[44:45], v[10:11]
	v_mov_b64_e32 v[42:43], v[8:9]
	v_mov_b64_e32 v[40:41], v[6:7]
	v_mov_b64_e32 v[38:39], v[4:5]
	v_mov_b64_e32 v[36:37], v[2:3]
	v_mov_b64_e32 v[34:35], v[0:1]
	v_mov_b64_e32 v[30:31], v[12:13]
	v_mov_b64_e32 v[28:29], v[10:11]
	v_mov_b64_e32 v[26:27], v[8:9]
	v_mov_b64_e32 v[24:25], v[6:7]
	v_mov_b64_e32 v[22:23], v[4:5]
	v_mov_b64_e32 v[20:21], v[2:3]
	v_mov_b64_e32 v[18:19], v[0:1]
	v_mov_b64_e32 v[16:17], v[14:15]
	v_add_u32_e32 v175, 6, v172
	v_add_u32_e32 v184, 5, v172
	s_mov_b32 s8, 0
	v_mov_b32_e32 v203, 0xf149f2ca
	v_mov_b32_e32 v150, v151
	v_mov_b32_e32 v185, 0xf149f2ca
	v_mov_b64_e32 v[14:15], v[12:13]
	v_mov_b64_e32 v[12:13], v[10:11]
	v_mov_b64_e32 v[10:11], v[8:9]
	v_mov_b64_e32 v[8:9], v[6:7]
	v_mov_b64_e32 v[6:7], v[4:5]
	v_mov_b64_e32 v[4:5], v[2:3]
	v_mov_b64_e32 v[2:3], v[0:1]
	s_mov_b32 s83, s4
	s_nop 0

.LBB0_642:
	s_nop 0
	v_and_b32_e32 v0, 3, v195
	s_lshl_b32 s74, s58, 1
	v_lshl_add_u64 v[66:67], v[178:179], 0, s[74:75]
	v_lshlrev_b32_e32 v0, 1, v0
	v_lshl_add_u64 v[66:67], v[66:67], 0, v[0:1]
	v_add_co_u32_e32 v66, vcc, 0x1000, v66
	s_movk_i32 s90, 0x1000
	s_nop 0
	v_addc_co_u32_e32 v67, vcc, 0, v67, vcc
	global_load_ushort v132, v[66:67], off offset:784
	v_lshl_add_u64 v[66:67], v[176:177], 0, s[74:75]
	v_lshl_add_u64 v[66:67], v[66:67], 0, v[0:1]
	v_add_co_u32_e32 v66, vcc, s90, v66
	v_lshl_add_u32 v133, v195, 2, s77
	s_nop 0
	v_addc_co_u32_e32 v67, vcc, 0, v67, vcc
	global_load_ushort v0, v[66:67], off offset:784
	v_mov_b32_e32 v67, v151
	v_mov_b32_e32 v66, v150
	s_nop 0
	v_permlane32_swap_b32_e32 v151, v67
	v_permlane32_swap_b32_e32 v150, v66
	v_pk_add_f32 v[66:67], v[150:151], v[66:67]
	ds_read2st64_b32 v[68:69], v133 offset1:1
	ds_read2st64_b32 v[70:71], v133 offset0:2 offset1:3
	ds_read2st64_b32 v[72:73], v133 offset0:4 offset1:5
	ds_read2st64_b32 v[74:75], v133 offset0:6 offset1:7
	ds_read2st64_b32 v[76:77], v133 offset0:8 offset1:9
	ds_read2st64_b32 v[78:79], v133 offset0:10 offset1:11
	ds_read2st64_b32 v[80:81], v133 offset0:12 offset1:13
	s_waitcnt vmcnt(0) lgkmcnt(0)
	ds_read2st64_b32 v[114:115], v133 offset0:14 offset1:15
	ds_read2st64_b32 v[116:117], v133 offset0:16 offset1:17
	ds_read2st64_b32 v[118:119], v133 offset0:18 offset1:19
	ds_read2st64_b32 v[120:121], v133 offset0:20 offset1:21
	ds_read2st64_b32 v[122:123], v133 offset0:22 offset1:23
	v_rcp_f32_e32 v134, v67
	v_cmp_lt_f32_e32 vcc, 0, v67
	ds_read2st64_b32 v[124:125], v133 offset0:24 offset1:25
	ds_read2st64_b32 v[126:127], v133 offset0:26 offset1:27
	ds_read2st64_b32 v[128:129], v133 offset0:28 offset1:29
	ds_read2st64_b32 v[130:131], v133 offset0:30 offset1:31
	s_add_i32 s4, s76, 0xd81
	v_cndmask_b32_e32 v67, 0, v134, vcc
	v_cmp_lt_f32_e32 vcc, 0, v66
	s_add_i32 s10, s76, 0xf8f
	s_andn2_b32 s4, s4, 31
	s_cmpk_gt_i32 s45, 0x1fe
	s_cselect_b32 s8, s4, 0
	s_mov_b64 s[4:5], -1
	s_cmp_le_i32 s8, s10
	s_movk_i32 s83, 0xfc00
	s_mov_b64 s[94:95], 0x80000
	s_mov_b64 s[96:97], 0x90000
	v_lshlrev_b32_e32 v132, 16, v132
	v_mul_f32_e32 v67, v67, v132
	v_fma_f32 v50, v50, v67, v68
	v_fmac_f32_e32 v69, v51, v67
	s_waitcnt lgkmcnt(7)
	v_fmac_f32_e32 v117, v35, v67
	s_waitcnt lgkmcnt(6)
	v_fma_f32 v35, v36, v67, v118
	v_fma_f32 v51, v52, v67, v70
	v_fmac_f32_e32 v71, v53, v67
	v_fma_f32 v52, v54, v67, v72
	v_fmac_f32_e32 v73, v55, v67
	v_fma_f32 v53, v56, v67, v74
	v_fmac_f32_e32 v75, v57, v67
	v_fma_f32 v54, v58, v67, v76
	v_fmac_f32_e32 v77, v59, v67
	v_fma_f32 v55, v60, v67, v78
	v_fmac_f32_e32 v79, v61, v67
	v_fma_f32 v56, v62, v67, v80
	v_fmac_f32_e32 v81, v63, v67
	v_fma_f32 v57, v64, v67, v114
	v_fmac_f32_e32 v115, v65, v67
	v_fma_f32 v34, v34, v67, v116
	v_fmac_f32_e32 v119, v37, v67
	s_waitcnt lgkmcnt(5)
	v_fma_f32 v36, v38, v67, v120
	v_fmac_f32_e32 v121, v39, v67
	s_waitcnt lgkmcnt(4)
	v_fma_f32 v37, v40, v67, v122
	v_fmac_f32_e32 v123, v41, v67
	s_waitcnt lgkmcnt(3)
	v_fma_f32 v38, v42, v67, v124
	v_fmac_f32_e32 v125, v43, v67
	s_waitcnt lgkmcnt(2)
	v_fma_f32 v39, v44, v67, v126
	v_fmac_f32_e32 v127, v45, v67
	ds_write2st64_b32 v133, v50, v69 offset1:1
	ds_write2st64_b32 v133, v51, v71 offset0:2 offset1:3
	ds_write2st64_b32 v133, v52, v73 offset0:4 offset1:5
	ds_write2st64_b32 v133, v53, v75 offset0:6 offset1:7
	ds_write2st64_b32 v133, v54, v77 offset0:8 offset1:9
	ds_write2st64_b32 v133, v55, v79 offset0:10 offset1:11
	ds_write2st64_b32 v133, v56, v81 offset0:12 offset1:13
	ds_write2st64_b32 v133, v57, v115 offset0:14 offset1:15
	ds_write2st64_b32 v133, v34, v117 offset0:16 offset1:17
	ds_write2st64_b32 v133, v35, v119 offset0:18 offset1:19
	ds_write2st64_b32 v133, v36, v121 offset0:20 offset1:21
	ds_write2st64_b32 v133, v37, v123 offset0:22 offset1:23
	ds_write2st64_b32 v133, v38, v125 offset0:24 offset1:25
	ds_write2st64_b32 v133, v39, v127 offset0:26 offset1:27
	v_rcp_f32_e32 v35, v66
	s_waitcnt lgkmcnt(14)
	v_fma_f32 v34, v46, v67, v128
	v_fmac_f32_e32 v129, v47, v67
	ds_write2st64_b32 v133, v34, v129 offset0:28 offset1:29
	v_fma_f32 v34, v48, v67, v130
	v_fmac_f32_e32 v131, v49, v67
	ds_write2st64_b32 v133, v34, v131 offset0:30 offset1:31
	v_cndmask_b32_e32 v36, 0, v35, vcc
	ds_read2st64_b32 v[34:35], v133 offset0:32 offset1:33
	v_lshlrev_b32_e32 v0, 16, v0
	v_mul_f32_e32 v0, v36, v0
	ds_read2st64_b32 v[36:37], v133 offset0:34 offset1:35
	ds_read2st64_b32 v[38:39], v133 offset0:36 offset1:37
	ds_read2st64_b32 v[40:41], v133 offset0:38 offset1:39
	s_waitcnt lgkmcnt(3)
	v_fma_f32 v18, v18, v0, v34
	v_fmac_f32_e32 v35, v19, v0
	ds_write2st64_b32 v133, v18, v35 offset0:32 offset1:33
	s_waitcnt lgkmcnt(3)
	v_fma_f32 v18, v20, v0, v36
	v_fmac_f32_e32 v37, v21, v0
	ds_write2st64_b32 v133, v18, v37 offset0:34 offset1:35
	s_waitcnt lgkmcnt(3)
	v_fma_f32 v18, v22, v0, v38
	v_fmac_f32_e32 v39, v23, v0
	ds_write2st64_b32 v133, v18, v39 offset0:36 offset1:37
	ds_read2st64_b32 v[18:19], v133 offset0:40 offset1:41
	s_waitcnt lgkmcnt(4)
	v_fma_f32 v20, v24, v0, v40
	v_fmac_f32_e32 v41, v25, v0
	ds_write2st64_b32 v133, v20, v41 offset0:38 offset1:39
	ds_read2st64_b32 v[20:21], v133 offset0:42 offset1:43
	ds_read2st64_b32 v[22:23], v133 offset0:44 offset1:45
	ds_read2st64_b32 v[24:25], v133 offset0:46 offset1:47
	s_waitcnt lgkmcnt(4)
	v_fma_f32 v18, v26, v0, v18
	v_fmac_f32_e32 v19, v27, v0
	ds_write2st64_b32 v133, v18, v19 offset0:40 offset1:41
	s_waitcnt lgkmcnt(3)
	v_fma_f32 v18, v28, v0, v20
	v_fmac_f32_e32 v21, v29, v0
	ds_write2st64_b32 v133, v18, v21 offset0:42 offset1:43
	s_waitcnt lgkmcnt(3)
	v_fma_f32 v18, v30, v0, v22
	v_fmac_f32_e32 v23, v31, v0
	ds_write2st64_b32 v133, v18, v23 offset0:44 offset1:45
	ds_read2st64_b32 v[18:19], v133 offset0:48 offset1:49
	s_waitcnt lgkmcnt(4)
	v_fma_f32 v20, v32, v0, v24
	v_fmac_f32_e32 v25, v33, v0
	ds_write2st64_b32 v133, v20, v25 offset0:46 offset1:47
	ds_read2st64_b32 v[20:21], v133 offset0:50 offset1:51
	ds_read2st64_b32 v[22:23], v133 offset0:52 offset1:53
	ds_read2st64_b32 v[24:25], v133 offset0:54 offset1:55
	s_waitcnt lgkmcnt(4)
	v_fma_f32 v2, v2, v0, v18
	v_fmac_f32_e32 v19, v3, v0
	ds_write2st64_b32 v133, v2, v19 offset0:48 offset1:49
	s_waitcnt lgkmcnt(3)
	v_fma_f32 v2, v4, v0, v20
	v_fmac_f32_e32 v21, v5, v0
	ds_write2st64_b32 v133, v2, v21 offset0:50 offset1:51
	s_waitcnt lgkmcnt(3)
	v_fma_f32 v2, v6, v0, v22
	v_fmac_f32_e32 v23, v7, v0
	ds_write2st64_b32 v133, v2, v23 offset0:52 offset1:53
	ds_read2st64_b32 v[2:3], v133 offset0:56 offset1:57
	s_waitcnt lgkmcnt(4)
	v_fma_f32 v4, v8, v0, v24
	v_fmac_f32_e32 v25, v9, v0
	ds_write2st64_b32 v133, v4, v25 offset0:54 offset1:55
	ds_read2st64_b32 v[4:5], v133 offset0:58 offset1:59
	ds_read2st64_b32 v[6:7], v133 offset0:60 offset1:61
	ds_read2st64_b32 v[8:9], v133 offset0:62 offset1:63
	s_waitcnt lgkmcnt(4)
	v_fma_f32 v2, v10, v0, v2
	v_fmac_f32_e32 v3, v11, v0
	ds_write2st64_b32 v133, v2, v3 offset0:56 offset1:57
	s_waitcnt lgkmcnt(3)
	v_fma_f32 v2, v12, v0, v4
	v_fmac_f32_e32 v5, v13, v0
	ds_write2st64_b32 v133, v2, v5 offset0:58 offset1:59
	s_waitcnt lgkmcnt(3)
	v_fma_f32 v2, v14, v0, v6
	v_fmac_f32_e32 v7, v15, v0
	ds_write2st64_b32 v133, v2, v7 offset0:60 offset1:61
	s_waitcnt lgkmcnt(3)
	v_fma_f32 v2, v16, v0, v8
	v_fmac_f32_e32 v9, v17, v0
	ds_write2st64_b32 v133, v2, v9 offset0:62 offset1:63
	s_nop 0
	v_ashrrev_i32_e32 v2, 5, v195
	v_lshlrev_b32_e32 v151, 2, v2
	s_cbranch_scc0 .LBB0_657
	v_and_b32_e32 v3, 31, v195
	v_mul_u32_u24_e32 v0, 0xa00, v3
	v_lshlrev_b32_e32 v6, 3, v2
	v_lshlrev_b32_e32 v0, 1, v0
	v_ashrrev_i32_e32 v7, 31, v6
	v_lshl_add_u64 v[4:5], v[148:149], 0, v[0:1]
	v_lshlrev_b64 v[6:7], 1, v[6:7]
	v_lshl_add_u64 v[148:149], v[4:5], 0, v[6:7]
	v_mad_i64_i32 v[4:5], s[4:5], s8, v247, v[148:149]
	global_load_dwordx4 v[114:117], v[4:5], off offset:2144
	global_load_dwordx4 v[118:121], v[4:5], off offset:2112
	global_load_dwordx4 v[122:125], v[4:5], off offset:2080
	global_load_dwordx4 v[126:129], v[4:5], off offset:2048
	s_add_i32 s4, s82, 16
	s_ashr_i32 s9, s8, 31
	s_ashr_i32 s5, s4, 31
	s_lshl_b64 s[4:5], s[4:5], 19
	s_addk_i32 s76, 0xd8f
	s_lshl_b64 s[6:7], s[8:9], 7
	s_add_u32 s4, s4, s6
	s_addc_u32 s5, s5, s7
	v_lshlrev_b32_e32 v0, 5, v3
	v_lshlrev_b32_e32 v150, 2, v2
	v_lshl_add_u64 v[2:3], s[4:5], 0, v[0:1]
	v_lshl_add_u64 v[2:3], v[2:3], 0, v[6:7]
	v_mov_b32_e32 v14, v1
	v_mov_b32_e32 v15, v1
	v_lshl_add_u64 v[152:153], v[164:165], 0, v[2:3]
	v_mov_b32_e32 v0, v1
	v_mov_b32_e32 v2, v1
	v_mov_b32_e32 v3, v1
	v_mov_b32_e32 v4, v1
	v_mov_b32_e32 v5, v1
	v_mov_b32_e32 v6, v1
	v_mov_b32_e32 v7, v1
	v_mov_b32_e32 v8, v1
	v_mov_b32_e32 v9, v1
	v_mov_b32_e32 v10, v1
	v_mov_b32_e32 v11, v1
	v_mov_b32_e32 v12, v1
	v_mov_b32_e32 v13, v1
	v_mov_b64_e32 v[64:65], v[14:15]
	v_mov_b64_e32 v[48:49], v[14:15]
	v_mov_b64_e32 v[32:33], v[14:15]
	v_mov_b64_e32 v[62:63], v[12:13]
	v_mov_b64_e32 v[60:61], v[10:11]
	v_mov_b64_e32 v[58:59], v[8:9]
	v_mov_b64_e32 v[56:57], v[6:7]
	v_mov_b64_e32 v[54:55], v[4:5]
	v_mov_b64_e32 v[52:53], v[2:3]
	v_mov_b64_e32 v[50:51], v[0:1]
	v_mov_b64_e32 v[46:47], v[12:13]
	v_mov_b64_e32 v[44:45], v[10:11]
	v_mov_b64_e32 v[42:43], v[8:9]
	v_mov_b64_e32 v[40:41], v[6:7]
	v_mov_b64_e32 v[38:39], v[4:5]
	v_mov_b64_e32 v[36:37], v[2:3]
	v_mov_b64_e32 v[34:35], v[0:1]
	v_mov_b64_e32 v[30:31], v[12:13]
	v_mov_b64_e32 v[28:29], v[10:11]
	v_mov_b64_e32 v[26:27], v[8:9]
	v_mov_b64_e32 v[24:25], v[6:7]
	v_mov_b64_e32 v[22:23], v[4:5]
	v_mov_b64_e32 v[20:21], v[2:3]
	v_mov_b64_e32 v[18:19], v[0:1]
	v_mov_b64_e32 v[16:17], v[14:15]
	v_add_u32_e32 v173, 0xfffffe00, v172
	v_add_u32_e32 v175, 0xfffffe08, v172
	v_mov_b32_e32 v202, 0xf149f2ca
	v_mov_b32_e32 v147, 0
	v_mov_b32_e32 v146, 0
	v_mov_b32_e32 v180, 0xf149f2ca
	v_mov_b64_e32 v[14:15], v[12:13]
	v_mov_b64_e32 v[12:13], v[10:11]
	v_mov_b64_e32 v[10:11], v[8:9]
	v_mov_b64_e32 v[8:9], v[6:7]
	v_mov_b64_e32 v[6:7], v[4:5]
	v_mov_b64_e32 v[4:5], v[2:3]
	v_mov_b64_e32 v[2:3], v[0:1]
